# XCD-local barriers after G2/G3/G4 (placement-guarded), rest = stack14
# baseline (speedup 1.0000x reference)
; #define LAS __attribute__((address_space(3)))
; __device__ __forceinline__ unsigned xb_add(unsigned* p, unsigned v) { return __hip_atomic_fetch_add(p, v, __ATOMIC_RELAXED, __HIP_MEMORY_SCOPE_AGENT); }
; __device__ __forceinline__ unsigned xb_xcc_id() { return (unsigned)__builtin_amdgcn_s_getreg((3 << 11) | 20) & 0xFu; }
; __device__ __forceinline__ XcdBarrier xcd_barrier_post(unsigned* bar, volatile LAS unsigned* st) {
;     XcdBarrier b; b.bar = bar; b.x = xb_xcc_id(); b.st = st;
;     if (threadIdx.x == 0) (void)xb_add(&bar[XB_XCNT(b.x)], 1u);
;     return b;
; }
.LBB0_93:
	s_waitcnt lgkmcnt(0)
	v_readfirstlane_b32 s99, v3
	v_readfirstlane_b32 s100, v1
	s_and_b32 s98, s67, 7
	s_cmp_lg_u32 s98, s2
	s_cselect_b32 s98, 1, 0
	s_cmp_lg_u32 s99, 32
	s_cselect_b32 s99, 1, 0
	s_cmp_lg_u32 s100, 8
	s_cselect_b32 s100, 1, 0
	s_or_b32 s98, s98, s99
	s_or_b32 s98, s98, s100
	s_cmp_eq_u32 s98, 0
	s_cbranch_scc1 .Lxg_ok
	v_readlane_b32 s100, v252, 8
	v_readlane_b32 s101, v252, 9
	v_mov_b32_e32 v6, 0x3600
	v_mov_b32_e32 v7, 1
	s_nop 4
	global_atomic_or v6, v7, s[100:101]
	s_waitcnt vmcnt(0)

; __device__ __forceinline__ void xcd_barrier(const XcdBarrier& b) {
;     ...
;         unsigned nloc = b.st[0], nx = b.st[1];
;         if (nloc == 0u) { xcd_barrier_complete(bar, b.x, nloc, nx); b.st[0] = nloc; b.st[1] = nx; }
.Lxb_p0_done:
	v_mov_b32_e32 v9, 0x3600
	global_load_dword v6, v9, s[98:99] sc1
	v_mov_b32_e32 v9, 0x21ff8
	s_waitcnt vmcnt(0)
	ds_write_b32 v9, v6

; __device__ __forceinline__ unsigned xb_ld(unsigned* p)              { return __hip_atomic_load(p, __ATOMIC_RELAXED, __HIP_MEMORY_SCOPE_AGENT); }
; __device__ __forceinline__ unsigned xb_add(unsigned* p, unsigned v) { return __hip_atomic_fetch_add(p, v, __ATOMIC_RELAXED, __HIP_MEMORY_SCOPE_AGENT); }
; #define XB_SPIN(cond, bar) do { unsigned _sp = 0; while (cond) { __builtin_amdgcn_s_sleep(1); \
;     if ((++_sp & 255u) == 0u) { if (xb_ld(&(bar)[XB_TMO])) break; if (_sp > XB_SPIN_CAP) { atomicAdd(&(bar)[XB_TMO], 1u); break; } } } } while (0)
; __device__ __forceinline__ void xcd_barrier(const XcdBarrier& b) {
;     ...
;     if (threadIdx.x == 0) {
;         unsigned* bar = b.bar;
;         __builtin_amdgcn_s_waitcnt(0);
;         unsigned nloc = b.st[0], nx = b.st[1];
;         if (nloc == 0u) { xcd_barrier_complete(bar, b.x, nloc, nx); b.st[0] = nloc; b.st[1] = nx; }
;         const unsigned old = xb_add(&bar[XB_XSUB(b.x)], 1u);
;         const unsigned gen = old / nloc;
;         if (old + 1u == (gen + 1u) * nloc) {
;             __builtin_amdgcn_fence(__ATOMIC_RELEASE, "agent");
;             asm volatile("s_waitcnt vmcnt(0)" ::: "memory");
;             const unsigned og = xb_add(&bar[XB_TOP], 1u);
;             const unsigned tg = og / nx;
;             if (og + 1u == (tg + 1u) * nx) xb_add(&bar[XB_TOPGEN], 1u);
;             else XB_SPIN(xb_ld(&bar[XB_TOPGEN]) == tg, bar);
;             __builtin_amdgcn_fence(__ATOMIC_ACQUIRE, "agent");
;             asm volatile("s_waitcnt vmcnt(0)" ::: "memory");
;         } else {
;             XB_SPIN(xb_ld(&bar[XB_TOPGEN]) == gen, bar);
;             __builtin_amdgcn_fence(__ATOMIC_ACQUIRE, "agent");
;             asm volatile("s_waitcnt vmcnt(0)" ::: "memory");
;         }
.LBB0_610:
	v_readlane_b32 s4, v253, 35
	v_readlane_b32 s5, v253, 36
	v_cvt_f32_u32_e32 v1, v2
	v_sub_u32_e32 v4, 0, v2
	v_rcp_iflag_f32_e32 v1, v1
	s_nop 1
	global_atomic_add v3, v177, v238, s[4:5] sc0
	v_mul_f32_e32 v1, 0x4f7ffffe, v1
	v_cvt_u32_f32_e32 v1, v1
	v_mul_lo_u32 v4, v4, v1
	v_mul_hi_u32 v4, v1, v4
	v_add_u32_e32 v1, v1, v4
	s_waitcnt vmcnt(0)
	v_mul_hi_u32 v1, v3, v1
	v_mul_lo_u32 v4, v1, v2
	v_sub_u32_e32 v4, v3, v4
	v_add_u32_e32 v5, 1, v1
	v_cmp_ge_u32_e32 vcc, v4, v2
	v_add_u32_e32 v3, 1, v3
	s_nop 0
	v_cndmask_b32_e32 v1, v1, v5, vcc
	v_sub_u32_e32 v5, v4, v2
	v_cndmask_b32_e32 v4, v4, v5, vcc
	v_add_u32_e32 v5, 1, v1
	v_cmp_ge_u32_e32 vcc, v4, v2
	s_nop 1
	v_cndmask_b32_e32 v1, v1, v5, vcc
	v_mul_lo_u32 v4, v2, v1
	v_add_u32_e32 v2, v4, v2
	v_cmp_ne_u32_e32 vcc, v3, v2
	s_waitcnt lgkmcnt(0)
	v_add_u32_e32 v4, 1, v1
	v_mul_lo_u32 v4, v4, v0
	v_mov_b32_e32 v6, 0x21ff8
	ds_read_b32 v6, v6
	v_readlane_b32 s98, v253, 39
	v_readlane_b32 s99, v253, 40
	s_nop 4
	s_waitcnt lgkmcnt(0)
	v_readfirstlane_b32 s100, v6
	s_cmp_eq_u32 s100, 0
	s_cbranch_scc0 .Lxb_b3_full
	s_cbranch_vccnz .Lxb_b3_lnl
	buffer_inv sc1
	s_waitcnt vmcnt(0)
	global_atomic_add v177, v238, s[98:99]
	s_branch .Lxb_b3_done
.Lxb_b3_lnl:
	buffer_inv sc1
	s_mov_b32 s100, 0
.Lxb_b3_lspin:
	global_load_dword v5, v177, s[4:5] sc1
	s_waitcnt vmcnt(0)
	v_cmp_ge_u32_e32 vcc, v5, v2
	s_cbranch_vccnz .Lxb_b3_done
	s_sleep 1
	s_add_i32 s100, s100, 1
	s_cmp_lt_u32 s100, 0x40000
	s_cbranch_scc1 .Lxb_b3_lspin
	s_branch .Lxb_b3_done
.Lxb_b3_full:
	s_cbranch_vccnz .Lxb_b3_nl
	buffer_wbl2 sc1
	s_waitcnt vmcnt(0)
	global_atomic_add v177, v238, s[98:99]
	buffer_inv sc1
	s_branch .Lxb_b3_poll
